# GEMM residual epilogue (bf16 source): loads software-pipelined three row groups ahead instead of four serial round trips
# speedup vs baseline: 1.0102x; 1.0005x over previous
; DEV unsigned pk_bf16(float lo, float hi) { unsigned r; asm("v_cvt_pk_bf16_f32 %0, %1, %2" : "=v"(r) : "v"(lo), "v"(hi)); return r; }
; DEV float bflo(unsigned w) { return __uint_as_float(w << 16); }
; DEV float bfhi(unsigned w) { return __uint_as_float(w & 0xffff0000u); }
;   DEV void operator()(const f32x4 (&acc)[2][2][4][2], const Unit& u, int wr, int wc, int fr, int fq) const {
;     ...
; #pragma unroll
;         for (int ai = 0; ai < 2; ++ai)
; #pragma unroll
;           for (int mp = 0; mp < 2; ++mp) {
;             u32x4 x[4];
; #pragma unroll
;             for (int c = 0; c < 4; ++c) x[c] = *(const u32x4*)(xb + (size_t)(row00 + ai * HALF + (2 * mp + (c >> 1)) * 16) * 1024 + col00 + (c & 1) * HALF);
; #pragma unroll
;             for (int c = 0; c < 4; ++c) {
;               const f32x4 a0 = acc[ai][c & 1][2 * mp + (c >> 1)][0], a1 = acc[ai][c & 1][2 * mp + (c >> 1)][1], g0 = g[c & 1][0], g1 = g[c & 1][1];
;               const u32x4 w = x[c];
;               *(u32x4*)(xb + (size_t)(row00 + ai * HALF + (2 * mp + (c >> 1)) * 16) * 1024 + col00 + (c & 1) * HALF) =
;                   (u32x4){pk_bf16(bflo(w.x) + g0[0] * a0[0], bfhi(w.x) + g0[1] * a0[1]), pk_bf16(bflo(w.y) + g0[2] * a0[2], bfhi(w.y) + g0[3] * a0[3]),
;                           pk_bf16(bflo(w.z) + g1[0] * a1[0], bfhi(w.z) + g1[1] * a1[1]), pk_bf16(bflo(w.w) + g1[2] * a1[2], bfhi(w.w) + g1[3] * a1[3])};
.LBB0_641:
	v_lshl_add_u64 v[148:149], s[88:89], 0, v[154:155]
	v_lshlrev_b64 v[146:147], 11, v[196:197]
	s_mov_b64 s[42:43], 0x8000
	s_mov_b64 s[10:11], 0x28000
	v_lshl_add_u64 v[148:149], v[148:149], 0, v[146:147]
	v_lshl_add_u64 v[146:147], v[148:149], 0, 0
	global_load_dwordx4 v[152:155], v[146:147], off
	global_load_dwordx4 v[156:159], v[146:147], off offset:256
	v_lshl_add_u64 v[146:147], v[146:147], 0, s[42:43]
	global_load_dwordx4 v[160:163], v[146:147], off
	global_load_dwordx4 v[164:167], v[146:147], off offset:256
	v_lshl_add_u64 v[146:147], v[146:147], 0, s[42:43]
	global_load_dwordx4 v[168:171], v[146:147], off
	global_load_dwordx4 v[172:175], v[146:147], off offset:256
	v_lshl_add_u64 v[146:147], v[146:147], 0, s[42:43]
	s_waitcnt vmcnt(4)
	v_lshlrev_b32_e32 v40, 16, v152
	v_and_b32_e32 v150, 0xffff0000, v152
	v_fmac_f32_e32 v40, v126, v142
	v_fmac_f32_e32 v150, v127, v143
	v_cvt_pk_bf16_f32 v152, v40, v150
	v_lshlrev_b32_e32 v40, 16, v153
	v_and_b32_e32 v151, 0xffff0000, v153
	v_fmac_f32_e32 v40, v128, v144
	v_fmac_f32_e32 v151, v129, v145
	v_cvt_pk_bf16_f32 v153, v40, v151
	v_lshlrev_b32_e32 v40, 16, v154
	v_and_b32_e32 v150, 0xffff0000, v154
	v_fmac_f32_e32 v40, v122, v138
	v_fmac_f32_e32 v150, v123, v139
	v_cvt_pk_bf16_f32 v154, v40, v150
	v_lshlrev_b32_e32 v40, 16, v155
	v_and_b32_e32 v151, 0xffff0000, v155
	v_fmac_f32_e32 v40, v124, v140
	v_fmac_f32_e32 v151, v125, v141
	v_cvt_pk_bf16_f32 v155, v40, v151
	v_lshlrev_b32_e32 v40, 16, v156
	v_and_b32_e32 v150, 0xffff0000, v156
	v_fmac_f32_e32 v40, v114, v134
	v_fmac_f32_e32 v150, v115, v135
	v_cvt_pk_bf16_f32 v156, v40, v150
	v_lshlrev_b32_e32 v40, 16, v157
	v_and_b32_e32 v151, 0xffff0000, v157
	v_fmac_f32_e32 v40, v116, v136
	v_fmac_f32_e32 v151, v117, v137
	v_cvt_pk_bf16_f32 v157, v40, v151
	v_lshlrev_b32_e32 v40, 16, v158
	v_and_b32_e32 v150, 0xffff0000, v158
	v_fmac_f32_e32 v40, v106, v130
	v_fmac_f32_e32 v150, v107, v131
	v_cvt_pk_bf16_f32 v158, v40, v150
	v_lshlrev_b32_e32 v40, 16, v159
	v_and_b32_e32 v151, 0xffff0000, v159
	v_fmac_f32_e32 v40, v108, v132
	v_fmac_f32_e32 v151, v109, v133
	v_cvt_pk_bf16_f32 v159, v40, v151
	global_store_dwordx4 v[148:149], v[152:155], off
	global_store_dwordx4 v[148:149], v[156:159], off offset:256
	v_lshl_add_u64 v[148:149], v[148:149], 0, s[42:43]
	global_load_dwordx4 v[126:129], v[146:147], off
	global_load_dwordx4 v[122:125], v[146:147], off offset:256
	v_lshl_add_u64 v[146:147], v[146:147], 0, s[10:11]
	global_load_dwordx4 v[114:117], v[146:147], off
	global_load_dwordx4 v[106:109], v[146:147], off offset:256
	v_lshl_add_u64 v[146:147], v[146:147], 0, s[42:43]
	s_waitcnt vmcnt(8)
	v_lshlrev_b32_e32 v40, 16, v160
	v_and_b32_e32 v150, 0xffff0000, v160
	v_fmac_f32_e32 v40, v118, v142
	v_fmac_f32_e32 v150, v119, v143
	v_cvt_pk_bf16_f32 v160, v40, v150
	v_lshlrev_b32_e32 v40, 16, v161
	v_and_b32_e32 v151, 0xffff0000, v161
	v_fmac_f32_e32 v40, v120, v144
	v_fmac_f32_e32 v151, v121, v145
	v_cvt_pk_bf16_f32 v161, v40, v151
	v_lshlrev_b32_e32 v40, 16, v162
	v_and_b32_e32 v150, 0xffff0000, v162
	v_fmac_f32_e32 v40, v110, v138
	v_fmac_f32_e32 v150, v111, v139
	v_cvt_pk_bf16_f32 v162, v40, v150
	v_lshlrev_b32_e32 v40, 16, v163
	v_and_b32_e32 v151, 0xffff0000, v163
	v_fmac_f32_e32 v40, v112, v140
	v_fmac_f32_e32 v151, v113, v141
	v_cvt_pk_bf16_f32 v163, v40, v151
	v_lshlrev_b32_e32 v40, 16, v164
	v_and_b32_e32 v150, 0xffff0000, v164
	v_fmac_f32_e32 v40, v102, v134
	v_fmac_f32_e32 v150, v103, v135
	v_cvt_pk_bf16_f32 v164, v40, v150
	v_lshlrev_b32_e32 v40, 16, v165
	v_and_b32_e32 v151, 0xffff0000, v165
	v_fmac_f32_e32 v40, v104, v136
	v_fmac_f32_e32 v151, v105, v137
	v_cvt_pk_bf16_f32 v165, v40, v151
	v_lshlrev_b32_e32 v40, 16, v166
	v_and_b32_e32 v150, 0xffff0000, v166
	v_fmac_f32_e32 v40, v98, v130
	v_fmac_f32_e32 v150, v99, v131
	v_cvt_pk_bf16_f32 v166, v40, v150
	v_lshlrev_b32_e32 v40, 16, v167
	v_and_b32_e32 v151, 0xffff0000, v167
	v_fmac_f32_e32 v40, v100, v132
	v_fmac_f32_e32 v151, v101, v133
	v_cvt_pk_bf16_f32 v167, v40, v151
	global_store_dwordx4 v[148:149], v[160:163], off
	global_store_dwordx4 v[148:149], v[164:167], off offset:256
	v_lshl_add_u64 v[148:149], v[148:149], 0, s[42:43]
	global_load_dwordx4 v[118:121], v[146:147], off
	global_load_dwordx4 v[110:113], v[146:147], off offset:256
	v_lshl_add_u64 v[146:147], v[146:147], 0, s[42:43]
	global_load_dwordx4 v[102:105], v[146:147], off
	global_load_dwordx4 v[98:101], v[146:147], off offset:256
	v_lshl_add_u64 v[146:147], v[146:147], 0, s[42:43]
	s_waitcnt vmcnt(12)
	v_lshlrev_b32_e32 v40, 16, v168
	v_and_b32_e32 v150, 0xffff0000, v168
	v_fmac_f32_e32 v40, v94, v142
	v_fmac_f32_e32 v150, v95, v143
	v_cvt_pk_bf16_f32 v168, v40, v150
	v_lshlrev_b32_e32 v40, 16, v169
	v_and_b32_e32 v151, 0xffff0000, v169
	v_fmac_f32_e32 v40, v96, v144
	v_fmac_f32_e32 v151, v97, v145
	v_cvt_pk_bf16_f32 v169, v40, v151
	v_lshlrev_b32_e32 v40, 16, v170
	v_and_b32_e32 v150, 0xffff0000, v170
	v_fmac_f32_e32 v40, v90, v138
	v_fmac_f32_e32 v150, v91, v139
	v_cvt_pk_bf16_f32 v170, v40, v150
	v_lshlrev_b32_e32 v40, 16, v171
	v_and_b32_e32 v151, 0xffff0000, v171
	v_fmac_f32_e32 v40, v92, v140
	v_fmac_f32_e32 v151, v93, v141
	v_cvt_pk_bf16_f32 v171, v40, v151
	v_lshlrev_b32_e32 v40, 16, v172
	v_and_b32_e32 v150, 0xffff0000, v172
	v_fmac_f32_e32 v40, v82, v134
	v_fmac_f32_e32 v150, v83, v135
	v_cvt_pk_bf16_f32 v172, v40, v150
	v_lshlrev_b32_e32 v40, 16, v173
	v_and_b32_e32 v151, 0xffff0000, v173
	v_fmac_f32_e32 v40, v84, v136
	v_fmac_f32_e32 v151, v85, v137
	v_cvt_pk_bf16_f32 v173, v40, v151
	v_lshlrev_b32_e32 v40, 16, v174
	v_and_b32_e32 v150, 0xffff0000, v174
	v_fmac_f32_e32 v40, v74, v130
	v_fmac_f32_e32 v150, v75, v131
	v_cvt_pk_bf16_f32 v174, v40, v150
	v_lshlrev_b32_e32 v40, 16, v175
	v_and_b32_e32 v151, 0xffff0000, v175
	v_fmac_f32_e32 v40, v76, v132
	v_fmac_f32_e32 v151, v77, v133
	v_cvt_pk_bf16_f32 v175, v40, v151
	global_store_dwordx4 v[148:149], v[168:171], off
	global_store_dwordx4 v[148:149], v[172:175], off offset:256
	v_lshl_add_u64 v[148:149], v[148:149], 0, s[42:43]
	global_load_dwordx4 v[94:97], v[146:147], off
	global_load_dwordx4 v[90:93], v[146:147], off offset:256
	s_waitcnt vmcnt(12)
; DEV unsigned pk_bf16(float lo, float hi) { unsigned r; asm("v_cvt_pk_bf16_f32 %0, %1, %2" : "=v"(r) : "v"(lo), "v"(hi)); return r; }
; DEV float bflo(unsigned w) { return __uint_as_float(w << 16); }
; DEV float bfhi(unsigned w) { return __uint_as_float(w & 0xffff0000u); }
;   DEV void operator()(const f32x4 (&acc)[2][2][4][2], const Unit& u, int wr, int wc, int fr, int fq) const {
;     ...
; #pragma unroll
;         for (int ai = 0; ai < 2; ++ai)
; #pragma unroll
;           for (int mp = 0; mp < 2; ++mp) {
;             u32x4 x[4];
; #pragma unroll
;             for (int c = 0; c < 4; ++c) x[c] = *(const u32x4*)(xb + (size_t)(row00 + ai * HALF + (2 * mp + (c >> 1)) * 16) * 1024 + col00 + (c & 1) * HALF);
; #pragma unroll
;             for (int c = 0; c < 4; ++c) {
;               const f32x4 a0 = acc[ai][c & 1][2 * mp + (c >> 1)][0], a1 = acc[ai][c & 1][2 * mp + (c >> 1)][1], g0 = g[c & 1][0], g1 = g[c & 1][1];
;               const u32x4 w = x[c];
;               *(u32x4*)(xb + (size_t)(row00 + ai * HALF + (2 * mp + (c >> 1)) * 16) * 1024 + col00 + (c & 1) * HALF) =
;                   (u32x4){pk_bf16(bflo(w.x) + g0[0] * a0[0], bfhi(w.x) + g0[1] * a0[1]), pk_bf16(bflo(w.y) + g0[2] * a0[2], bfhi(w.y) + g0[3] * a0[3]),
;                           pk_bf16(bflo(w.z) + g1[0] * a1[0], bfhi(w.z) + g1[1] * a1[1]), pk_bf16(bflo(w.w) + g1[2] * a1[2], bfhi(w.w) + g1[3] * a1[3])};
	v_lshlrev_b32_e32 v40, 16, v126
	v_and_b32_e32 v150, 0xffff0000, v126
	v_fmac_f32_e32 v40, v86, v142
	v_fmac_f32_e32 v150, v87, v143
	v_cvt_pk_bf16_f32 v126, v40, v150
	v_lshlrev_b32_e32 v40, 16, v127
	v_and_b32_e32 v151, 0xffff0000, v127
	v_fmac_f32_e32 v40, v88, v144
	v_fmac_f32_e32 v151, v89, v145
	v_cvt_pk_bf16_f32 v127, v40, v151
	v_lshlrev_b32_e32 v40, 16, v128
	v_and_b32_e32 v150, 0xffff0000, v128
	v_fmac_f32_e32 v40, v78, v138
	v_fmac_f32_e32 v150, v79, v139
	v_cvt_pk_bf16_f32 v128, v40, v150
	v_lshlrev_b32_e32 v40, 16, v129
	v_and_b32_e32 v151, 0xffff0000, v129
	v_fmac_f32_e32 v40, v80, v140
	v_fmac_f32_e32 v151, v81, v141
	v_cvt_pk_bf16_f32 v129, v40, v151
	v_lshlrev_b32_e32 v40, 16, v122
	v_and_b32_e32 v150, 0xffff0000, v122
	v_fmac_f32_e32 v40, v70, v134
	v_fmac_f32_e32 v150, v71, v135
	v_cvt_pk_bf16_f32 v122, v40, v150
	v_lshlrev_b32_e32 v40, 16, v123
	v_and_b32_e32 v151, 0xffff0000, v123
	v_fmac_f32_e32 v40, v72, v136
	v_fmac_f32_e32 v151, v73, v137
	v_cvt_pk_bf16_f32 v123, v40, v151
	v_lshlrev_b32_e32 v40, 16, v124
	v_and_b32_e32 v150, 0xffff0000, v124
	v_fmac_f32_e32 v40, v66, v130
	v_fmac_f32_e32 v150, v67, v131
	v_cvt_pk_bf16_f32 v124, v40, v150
	v_lshlrev_b32_e32 v40, 16, v125
	v_and_b32_e32 v151, 0xffff0000, v125
	v_fmac_f32_e32 v40, v68, v132
	v_fmac_f32_e32 v151, v69, v133
	v_cvt_pk_bf16_f32 v125, v40, v151
	global_store_dwordx4 v[148:149], v[126:129], off
	global_store_dwordx4 v[148:149], v[122:125], off offset:256
	v_lshl_add_u64 v[148:149], v[148:149], 0, s[10:11]
	s_waitcnt vmcnt(12)
	v_lshlrev_b32_e32 v40, 16, v114
	v_and_b32_e32 v150, 0xffff0000, v114
	v_fmac_f32_e32 v40, v62, v142
	v_fmac_f32_e32 v150, v63, v143
	v_cvt_pk_bf16_f32 v114, v40, v150
	v_lshlrev_b32_e32 v40, 16, v115
	v_and_b32_e32 v151, 0xffff0000, v115
	v_fmac_f32_e32 v40, v64, v144
	v_fmac_f32_e32 v151, v65, v145
	v_cvt_pk_bf16_f32 v115, v40, v151
	v_lshlrev_b32_e32 v40, 16, v116
	v_and_b32_e32 v150, 0xffff0000, v116
	v_fmac_f32_e32 v40, v58, v138
	v_fmac_f32_e32 v150, v59, v139
	v_cvt_pk_bf16_f32 v116, v40, v150
	v_lshlrev_b32_e32 v40, 16, v117
	v_and_b32_e32 v151, 0xffff0000, v117
	v_fmac_f32_e32 v40, v60, v140
	v_fmac_f32_e32 v151, v61, v141
	v_cvt_pk_bf16_f32 v117, v40, v151
	v_lshlrev_b32_e32 v40, 16, v106
	v_and_b32_e32 v150, 0xffff0000, v106
	v_fmac_f32_e32 v40, v50, v134
	v_fmac_f32_e32 v150, v51, v135
	v_cvt_pk_bf16_f32 v106, v40, v150
	v_lshlrev_b32_e32 v40, 16, v107
	v_and_b32_e32 v151, 0xffff0000, v107
	v_fmac_f32_e32 v40, v52, v136
	v_fmac_f32_e32 v151, v53, v137
	v_cvt_pk_bf16_f32 v107, v40, v151
	v_lshlrev_b32_e32 v40, 16, v108
	v_and_b32_e32 v150, 0xffff0000, v108
	v_fmac_f32_e32 v40, v42, v130
	v_fmac_f32_e32 v150, v43, v131
	v_cvt_pk_bf16_f32 v108, v40, v150
	v_lshlrev_b32_e32 v40, 16, v109
	v_and_b32_e32 v151, 0xffff0000, v109
	v_fmac_f32_e32 v40, v44, v132
	v_fmac_f32_e32 v151, v45, v133
	v_cvt_pk_bf16_f32 v109, v40, v151
	global_store_dwordx4 v[148:149], v[114:117], off
	global_store_dwordx4 v[148:149], v[106:109], off offset:256
	v_lshl_add_u64 v[148:149], v[148:149], 0, s[42:43]
	s_waitcnt vmcnt(10)
	v_lshlrev_b32_e32 v40, 16, v118
	v_and_b32_e32 v150, 0xffff0000, v118
	v_fmac_f32_e32 v40, v54, v142
	v_fmac_f32_e32 v150, v55, v143
	v_cvt_pk_bf16_f32 v118, v40, v150
	v_lshlrev_b32_e32 v40, 16, v119
	v_and_b32_e32 v151, 0xffff0000, v119
	v_fmac_f32_e32 v40, v56, v144
	v_fmac_f32_e32 v151, v57, v145
	v_cvt_pk_bf16_f32 v119, v40, v151
	v_lshlrev_b32_e32 v40, 16, v120
	v_and_b32_e32 v150, 0xffff0000, v120
	v_fmac_f32_e32 v40, v46, v138
	v_fmac_f32_e32 v150, v47, v139
	v_cvt_pk_bf16_f32 v120, v40, v150
	v_lshlrev_b32_e32 v40, 16, v121
	v_and_b32_e32 v151, 0xffff0000, v121
	v_fmac_f32_e32 v40, v48, v140
	v_fmac_f32_e32 v151, v49, v141
	v_cvt_pk_bf16_f32 v121, v40, v151
	v_lshlrev_b32_e32 v40, 16, v110
	v_and_b32_e32 v150, 0xffff0000, v110
	v_fmac_f32_e32 v40, v36, v134
	v_fmac_f32_e32 v150, v37, v135
	v_cvt_pk_bf16_f32 v110, v40, v150
	v_lshlrev_b32_e32 v40, 16, v111
	v_and_b32_e32 v151, 0xffff0000, v111
	v_fmac_f32_e32 v40, v38, v136
	v_fmac_f32_e32 v151, v39, v137
	v_cvt_pk_bf16_f32 v111, v40, v151
	v_lshlrev_b32_e32 v40, 16, v112
	v_and_b32_e32 v150, 0xffff0000, v112
	v_fmac_f32_e32 v40, v32, v130
	v_fmac_f32_e32 v150, v33, v131
	v_cvt_pk_bf16_f32 v112, v40, v150
	v_lshlrev_b32_e32 v40, 16, v113
	v_and_b32_e32 v151, 0xffff0000, v113
	v_fmac_f32_e32 v40, v34, v132
	v_fmac_f32_e32 v151, v35, v133
	v_cvt_pk_bf16_f32 v113, v40, v151
	global_store_dwordx4 v[148:149], v[118:121], off
	global_store_dwordx4 v[148:149], v[110:113], off offset:256
	v_lshl_add_u64 v[148:149], v[148:149], 0, s[42:43]
	s_waitcnt vmcnt(10)
; DEV unsigned pk_bf16(float lo, float hi) { unsigned r; asm("v_cvt_pk_bf16_f32 %0, %1, %2" : "=v"(r) : "v"(lo), "v"(hi)); return r; }
; DEV float bflo(unsigned w) { return __uint_as_float(w << 16); }
; DEV float bfhi(unsigned w) { return __uint_as_float(w & 0xffff0000u); }
;   DEV void operator()(const f32x4 (&acc)[2][2][4][2], const Unit& u, int wr, int wc, int fr, int fq) const {
;     ...
; #pragma unroll
;         for (int ai = 0; ai < 2; ++ai)
; #pragma unroll
;           for (int mp = 0; mp < 2; ++mp) {
;             u32x4 x[4];
; #pragma unroll
;             for (int c = 0; c < 4; ++c) x[c] = *(const u32x4*)(xb + (size_t)(row00 + ai * HALF + (2 * mp + (c >> 1)) * 16) * 1024 + col00 + (c & 1) * HALF);
; #pragma unroll
;             for (int c = 0; c < 4; ++c) {
;               const f32x4 a0 = acc[ai][c & 1][2 * mp + (c >> 1)][0], a1 = acc[ai][c & 1][2 * mp + (c >> 1)][1], g0 = g[c & 1][0], g1 = g[c & 1][1];
;               const u32x4 w = x[c];
;               *(u32x4*)(xb + (size_t)(row00 + ai * HALF + (2 * mp + (c >> 1)) * 16) * 1024 + col00 + (c & 1) * HALF) =
;                   (u32x4){pk_bf16(bflo(w.x) + g0[0] * a0[0], bfhi(w.x) + g0[1] * a0[1]), pk_bf16(bflo(w.y) + g0[2] * a0[2], bfhi(w.y) + g0[3] * a0[3]),
;                           pk_bf16(bflo(w.z) + g1[0] * a1[0], bfhi(w.z) + g1[1] * a1[1]), pk_bf16(bflo(w.w) + g1[2] * a1[2], bfhi(w.w) + g1[3] * a1[3])};
	v_lshlrev_b32_e32 v40, 16, v102
	v_and_b32_e32 v150, 0xffff0000, v102
	v_fmac_f32_e32 v40, v28, v142
	v_fmac_f32_e32 v150, v29, v143
	v_cvt_pk_bf16_f32 v102, v40, v150
	v_lshlrev_b32_e32 v40, 16, v103
	v_and_b32_e32 v151, 0xffff0000, v103
	v_fmac_f32_e32 v40, v30, v144
	v_fmac_f32_e32 v151, v31, v145
	v_cvt_pk_bf16_f32 v103, v40, v151
	v_lshlrev_b32_e32 v40, 16, v104
	v_and_b32_e32 v150, 0xffff0000, v104
	v_fmac_f32_e32 v40, v24, v138
	v_fmac_f32_e32 v150, v25, v139
	v_cvt_pk_bf16_f32 v104, v40, v150
	v_lshlrev_b32_e32 v40, 16, v105
	v_and_b32_e32 v151, 0xffff0000, v105
	v_fmac_f32_e32 v40, v26, v140
	v_fmac_f32_e32 v151, v27, v141
	v_cvt_pk_bf16_f32 v105, v40, v151
	v_lshlrev_b32_e32 v40, 16, v98
	v_and_b32_e32 v150, 0xffff0000, v98
	v_fmac_f32_e32 v40, v20, v134
	v_fmac_f32_e32 v150, v21, v135
	v_cvt_pk_bf16_f32 v98, v40, v150
	v_lshlrev_b32_e32 v40, 16, v99
	v_and_b32_e32 v151, 0xffff0000, v99
	v_fmac_f32_e32 v40, v22, v136
	v_fmac_f32_e32 v151, v23, v137
	v_cvt_pk_bf16_f32 v99, v40, v151
	v_lshlrev_b32_e32 v40, 16, v100
	v_and_b32_e32 v150, 0xffff0000, v100
	v_fmac_f32_e32 v40, v12, v130
	v_fmac_f32_e32 v150, v13, v131
	v_cvt_pk_bf16_f32 v100, v40, v150
	v_lshlrev_b32_e32 v40, 16, v101
	v_and_b32_e32 v151, 0xffff0000, v101
	v_fmac_f32_e32 v40, v14, v132
	v_fmac_f32_e32 v151, v15, v133
	v_cvt_pk_bf16_f32 v101, v40, v151
	global_store_dwordx4 v[148:149], v[102:105], off
	global_store_dwordx4 v[148:149], v[98:101], off offset:256
	v_lshl_add_u64 v[148:149], v[148:149], 0, s[42:43]
	s_waitcnt vmcnt(8)
	v_lshlrev_b32_e32 v40, 16, v94
	v_and_b32_e32 v150, 0xffff0000, v94
	v_fmac_f32_e32 v40, v16, v142
	v_fmac_f32_e32 v150, v17, v143
	v_cvt_pk_bf16_f32 v94, v40, v150
	v_lshlrev_b32_e32 v40, 16, v95
	v_and_b32_e32 v151, 0xffff0000, v95
	v_fmac_f32_e32 v40, v18, v144
	v_fmac_f32_e32 v151, v19, v145
	v_cvt_pk_bf16_f32 v95, v40, v151
	v_lshlrev_b32_e32 v40, 16, v96
	v_and_b32_e32 v150, 0xffff0000, v96
	v_fmac_f32_e32 v40, v8, v138
	v_fmac_f32_e32 v150, v9, v139
	v_cvt_pk_bf16_f32 v96, v40, v150
	v_lshlrev_b32_e32 v40, 16, v97
	v_and_b32_e32 v151, 0xffff0000, v97
	v_fmac_f32_e32 v40, v10, v140
	v_fmac_f32_e32 v151, v11, v141
	v_cvt_pk_bf16_f32 v97, v40, v151
	v_lshlrev_b32_e32 v40, 16, v90
	v_and_b32_e32 v150, 0xffff0000, v90
	v_fmac_f32_e32 v40, v4, v134
	v_fmac_f32_e32 v150, v5, v135
	v_cvt_pk_bf16_f32 v90, v40, v150
	v_lshlrev_b32_e32 v40, 16, v91
	v_and_b32_e32 v151, 0xffff0000, v91
	v_fmac_f32_e32 v40, v6, v136
	v_fmac_f32_e32 v151, v7, v137
	v_cvt_pk_bf16_f32 v91, v40, v151
	v_lshlrev_b32_e32 v40, 16, v92
	v_and_b32_e32 v150, 0xffff0000, v92
	v_fmac_f32_e32 v40, v0, v130
	v_fmac_f32_e32 v150, v1, v131
	v_cvt_pk_bf16_f32 v92, v40, v150
	v_lshlrev_b32_e32 v40, 16, v93
	v_and_b32_e32 v151, 0xffff0000, v93
	v_fmac_f32_e32 v40, v2, v132
	v_fmac_f32_e32 v151, v3, v133
	v_cvt_pk_bf16_f32 v93, v40, v151
	global_store_dwordx4 v[148:149], v[94:97], off
	v_lshlrev_b64 v[166:167], 11, v[196:197]
	s_mov_b64 s[10:11], 0x58000
	v_lshl_add_u64 v[166:167], v[166:167], 0, s[10:11]
	v_mov_b32_e32 v146, v90
	v_mov_b32_e32 v147, v91
	v_mov_b32_e32 v148, v92
	v_mov_b32_e32 v149, v93
